# v11 + f32 residual-stream stores of the fused LayerNorm epilogues (64 sites) made nontemporal
# speedup vs baseline: 1.0202x; 1.0071x over previous
.LBB0_85:
	s_or_b64 exec, exec, s[6:7]
	v_readlane_b32 s4, v253, 9
	s_add_i32 s4, s4, -6
	v_readlane_b32 s36, v254, 35
	v_readlane_b32 s5, v253, 10
	s_cmp_lt_u32 s4, 5
	v_readlane_b32 s50, v254, 49
	v_readlane_b32 s51, v254, 50
	v_readlane_b32 s6, v255, 7
	s_cselect_b32 s5, s51, s1
	s_cselect_b32 s4, s50, s0
	v_readlane_b32 s7, v255, 8
	s_lshl_b32 s6, s6, 11
	s_ashr_i32 s7, s6, 31
	v_readlane_b32 s46, v254, 45
	s_lshl_b64 s[6:7], s[6:7], 2
	v_readlane_b32 s47, v254, 46
	s_add_u32 s8, s46, s6
	v_readlane_b32 s48, v254, 47
	s_addc_u32 s9, s47, s7
	v_readlane_b32 s49, v254, 48
	s_add_u32 s6, s48, s6
	v_mov_b32_e32 v139, v129
	s_addc_u32 s7, s49, s7
	v_lshlrev_b64 v[134:135], 2, v[138:139]
	v_lshl_add_u64 v[140:141], s[8:9], 0, v[134:135]
	v_lshl_add_u64 v[142:143], s[6:7], 0, v[134:135]
	s_waitcnt lgkmcnt(0)
	s_barrier
	global_load_dwordx4 v[130:133], v[140:141], off
	global_load_dwordx4 v[134:137], v[142:143], off
	s_lshl_b32 s6, s24, 3
	s_add_i32 s6, s6, 0
	v_lshl_add_u32 v139, v144, 3, s6
	ds_read_b64 v[152:153], v139 offset:8192
	s_waitcnt lgkmcnt(0)
	v_cmp_eq_u32_e32 vcc, 0, v128
	v_lshl_add_u32 v128, v146, 11, v138
	v_mov_b32_e32 v147, 0x7fc00000
	v_lshl_add_u64 v[156:157], v[128:129], 2, s[4:5]
	v_sub_f32_e32 v93, v93, v152
	v_sub_f32_e32 v92, v92, v152
	v_sub_f32_e32 v95, v95, v152
	v_sub_f32_e32 v94, v94, v152
	v_pk_mul_f32 v[94:95], v[152:153], v[94:95] op_sel:[1,0]
	v_pk_mul_f32 v[92:93], v[152:153], v[92:93] op_sel:[1,0]
	v_readlane_b32 s6, v255, 9
	v_mov_b32_e32 v145, v129
	v_readlane_b32 s7, v255, 10
	v_add_u32_e32 v144, 0x8000, v128
	v_mov_b32_e32 v149, v129
	v_lshl_add_u64 v[152:153], v[128:129], 1, s[6:7]
	v_add_u32_e32 v148, 0x10000, v128
	v_mov_b32_e32 v151, v129
	v_add_u32_e32 v150, 0x18000, v128
	v_mov_b32_e32 v155, v129
	v_add_u32_e32 v154, 0x40000, v128
	v_readlane_b32 s37, v254, 36
	v_readlane_b32 s38, v254, 37
	v_readlane_b32 s39, v254, 38
	v_readlane_b32 s40, v254, 39
	v_readlane_b32 s41, v254, 40
	v_readlane_b32 s42, v254, 41
	v_readlane_b32 s43, v254, 42
	v_readlane_b32 s44, v254, 43
	v_readlane_b32 s45, v254, 44
	s_waitcnt vmcnt(0)
	v_pk_fma_f32 v[92:93], v[130:131], v[92:93], v[134:135]
	v_pk_fma_f32 v[94:95], v[132:133], v[94:95], v[136:137]
	v_cndmask_b32_e32 v93, v147, v93, vcc
	v_cndmask_b32_e32 v95, v147, v95, vcc
	v_cndmask_b32_e32 v94, v147, v94, vcc
	v_cndmask_b32_e32 v92, v147, v92, vcc
	global_store_dwordx4 v[156:157], v[92:95], off nt
	v_lshl_add_u64 v[156:157], v[144:145], 2, s[4:5]
	s_nop 0
	v_cvt_pk_bf16_f32 v92, v92, v93
	v_cvt_pk_bf16_f32 v93, v94, v95
	ds_read_b64 v[94:95], v139 offset:8320
	global_store_dwordx2 v[152:153], v[92:93], off
	v_lshl_add_u64 v[92:93], v[144:145], 1, s[6:7]
	s_waitcnt lgkmcnt(0)
	v_sub_f32_e32 v89, v89, v94
	v_sub_f32_e32 v88, v88, v94
	v_sub_f32_e32 v91, v91, v94
	v_sub_f32_e32 v90, v90, v94
	v_pk_mul_f32 v[90:91], v[94:95], v[90:91] op_sel:[1,0]
	v_pk_mul_f32 v[88:89], v[94:95], v[88:89] op_sel:[1,0]
	v_pk_fma_f32 v[90:91], v[132:133], v[90:91], v[136:137]
	v_pk_fma_f32 v[88:89], v[130:131], v[88:89], v[134:135]
	v_cndmask_b32_e32 v91, v147, v91, vcc
	v_cndmask_b32_e32 v90, v147, v90, vcc
	v_cndmask_b32_e32 v89, v147, v89, vcc
	v_cndmask_b32_e32 v88, v147, v88, vcc
	global_store_dwordx4 v[156:157], v[88:91], off nt
	v_lshl_add_u64 v[94:95], v[148:149], 2, s[4:5]
	s_nop 0
	v_cvt_pk_bf16_f32 v88, v88, v89
	v_cvt_pk_bf16_f32 v89, v90, v91
	ds_read_b64 v[90:91], v139 offset:8448
	global_store_dwordx2 v[92:93], v[88:89], off
	v_lshl_add_u64 v[88:89], v[148:149], 1, s[6:7]
	s_waitcnt lgkmcnt(0)
	v_sub_f32_e32 v85, v85, v90
	v_sub_f32_e32 v84, v84, v90
	v_sub_f32_e32 v87, v87, v90
	v_sub_f32_e32 v86, v86, v90
	v_pk_mul_f32 v[86:87], v[90:91], v[86:87] op_sel:[1,0]
	v_pk_mul_f32 v[84:85], v[90:91], v[84:85] op_sel:[1,0]
	v_pk_fma_f32 v[86:87], v[132:133], v[86:87], v[136:137]
	v_pk_fma_f32 v[84:85], v[130:131], v[84:85], v[134:135]
	v_cndmask_b32_e32 v87, v147, v87, vcc
	v_cndmask_b32_e32 v86, v147, v86, vcc
	v_cndmask_b32_e32 v85, v147, v85, vcc
	v_cndmask_b32_e32 v84, v147, v84, vcc
	global_store_dwordx4 v[94:95], v[84:87], off nt
	v_lshl_add_u64 v[90:91], v[150:151], 2, s[4:5]
	s_nop 0
	v_cvt_pk_bf16_f32 v84, v84, v85
	v_cvt_pk_bf16_f32 v85, v86, v87
	ds_read_b64 v[86:87], v139 offset:8576
	global_store_dwordx2 v[88:89], v[84:85], off
	v_lshl_add_u64 v[84:85], v[150:151], 1, s[6:7]
	s_waitcnt lgkmcnt(0)
	v_sub_f32_e32 v81, v81, v86
	v_sub_f32_e32 v80, v80, v86
	v_sub_f32_e32 v83, v83, v86
	v_sub_f32_e32 v82, v82, v86
	v_pk_mul_f32 v[82:83], v[86:87], v[82:83] op_sel:[1,0]
	v_pk_mul_f32 v[80:81], v[86:87], v[80:81] op_sel:[1,0]
	v_pk_fma_f32 v[82:83], v[132:133], v[82:83], v[136:137]
	v_pk_fma_f32 v[80:81], v[130:131], v[80:81], v[134:135]
	v_cndmask_b32_e32 v83, v147, v83, vcc
	v_cndmask_b32_e32 v82, v147, v82, vcc
	v_cndmask_b32_e32 v81, v147, v81, vcc
	v_cndmask_b32_e32 v80, v147, v80, vcc
	global_store_dwordx4 v[90:91], v[80:83], off nt
	v_lshl_add_u64 v[86:87], v[154:155], 2, s[4:5]
	s_nop 0
	v_cvt_pk_bf16_f32 v80, v80, v81
	v_cvt_pk_bf16_f32 v81, v82, v83
	ds_read_b64 v[82:83], v139 offset:9216
	global_store_dwordx2 v[84:85], v[80:81], off
	s_waitcnt lgkmcnt(0)
	v_sub_f32_e32 v81, v125, v82
	v_sub_f32_e32 v80, v124, v82
	v_sub_f32_e32 v85, v127, v82
	v_sub_f32_e32 v84, v126, v82
	v_pk_mul_f32 v[84:85], v[82:83], v[84:85] op_sel:[1,0]
	v_pk_mul_f32 v[80:81], v[82:83], v[80:81] op_sel:[1,0]
	v_pk_fma_f32 v[82:83], v[132:133], v[84:85], v[136:137]
	v_pk_fma_f32 v[80:81], v[130:131], v[80:81], v[134:135]
	v_cndmask_b32_e32 v83, v147, v83, vcc
	v_cndmask_b32_e32 v82, v147, v82, vcc
	v_cndmask_b32_e32 v81, v147, v81, vcc
	v_cndmask_b32_e32 v80, v147, v80, vcc
	global_store_dwordx4 v[86:87], v[80:83], off nt
	v_lshl_add_u64 v[86:87], v[154:155], 1, s[6:7]
	v_add_u32_e32 v84, 0x48000, v128
	v_cvt_pk_bf16_f32 v80, v80, v81
	v_cvt_pk_bf16_f32 v81, v82, v83
	ds_read_b64 v[82:83], v139 offset:9344
	global_store_dwordx2 v[86:87], v[80:81], off
	v_mov_b32_e32 v85, v129
	s_waitcnt lgkmcnt(0)
	v_sub_f32_e32 v81, v121, v82
	v_sub_f32_e32 v80, v120, v82
	v_sub_f32_e32 v87, v123, v82
	v_sub_f32_e32 v86, v122, v82
	v_pk_mul_f32 v[86:87], v[82:83], v[86:87] op_sel:[1,0]
	v_pk_mul_f32 v[80:81], v[82:83], v[80:81] op_sel:[1,0]
	v_pk_fma_f32 v[82:83], v[132:133], v[86:87], v[136:137]
	v_pk_fma_f32 v[80:81], v[130:131], v[80:81], v[134:135]
	v_cndmask_b32_e32 v83, v147, v83, vcc
	v_cndmask_b32_e32 v82, v147, v82, vcc
	v_cndmask_b32_e32 v81, v147, v81, vcc
	v_cndmask_b32_e32 v80, v147, v80, vcc
	v_lshl_add_u64 v[86:87], v[84:85], 2, s[4:5]
	global_store_dwordx4 v[86:87], v[80:83], off nt
	v_lshl_add_u64 v[84:85], v[84:85], 1, s[6:7]
	s_nop 0
	v_cvt_pk_bf16_f32 v80, v80, v81
	v_cvt_pk_bf16_f32 v81, v82, v83
	ds_read_b64 v[82:83], v139 offset:9472
	global_store_dwordx2 v[84:85], v[80:81], off
	v_add_u32_e32 v84, 0x50000, v128
	v_mov_b32_e32 v85, v129
	v_add_u32_e32 v128, 0x58000, v128
	s_waitcnt lgkmcnt(0)
	v_sub_f32_e32 v81, v117, v82
	v_sub_f32_e32 v80, v116, v82
	v_sub_f32_e32 v87, v119, v82
	v_sub_f32_e32 v86, v118, v82
	v_pk_mul_f32 v[86:87], v[82:83], v[86:87] op_sel:[1,0]
	v_pk_mul_f32 v[80:81], v[82:83], v[80:81] op_sel:[1,0]
	v_pk_fma_f32 v[82:83], v[132:133], v[86:87], v[136:137]
	v_pk_fma_f32 v[80:81], v[130:131], v[80:81], v[134:135]
	v_cndmask_b32_e32 v83, v147, v83, vcc
	v_cndmask_b32_e32 v82, v147, v82, vcc
	v_cndmask_b32_e32 v81, v147, v81, vcc
	v_cndmask_b32_e32 v80, v147, v80, vcc
	v_lshl_add_u64 v[86:87], v[84:85], 2, s[4:5]
	global_store_dwordx4 v[86:87], v[80:83], off nt
	v_lshl_add_u64 v[84:85], v[84:85], 1, s[6:7]
	s_nop 0
	v_cvt_pk_bf16_f32 v80, v80, v81
	v_cvt_pk_bf16_f32 v81, v82, v83
	ds_read_b64 v[82:83], v139 offset:9600
	global_store_dwordx2 v[84:85], v[80:81], off
	s_waitcnt lgkmcnt(0)
	v_sub_f32_e32 v81, v113, v82
	v_sub_f32_e32 v80, v112, v82
	v_sub_f32_e32 v85, v115, v82
	v_sub_f32_e32 v84, v114, v82
	v_pk_mul_f32 v[84:85], v[82:83], v[84:85] op_sel:[1,0]
	v_pk_mul_f32 v[80:81], v[82:83], v[80:81] op_sel:[1,0]
	v_pk_fma_f32 v[82:83], v[132:133], v[84:85], v[136:137]
	v_pk_fma_f32 v[80:81], v[130:131], v[80:81], v[134:135]
	v_cndmask_b32_e32 v83, v147, v83, vcc
	v_cndmask_b32_e32 v82, v147, v82, vcc
	v_cndmask_b32_e32 v81, v147, v81, vcc
	v_cndmask_b32_e32 v80, v147, v80, vcc
	v_lshl_add_u64 v[84:85], v[128:129], 2, s[4:5]
	global_store_dwordx4 v[84:85], v[80:83], off nt
	s_nop 1
	v_cvt_pk_bf16_f32 v80, v80, v81
	v_cvt_pk_bf16_f32 v81, v82, v83
	v_lshl_add_u64 v[82:83], v[128:129], 1, s[6:7]
	global_store_dwordx2 v[82:83], v[80:81], off
	global_load_dwordx4 v[80:83], v[140:141], off offset:64
	global_load_dwordx4 v[84:87], v[142:143], off offset:64
	ds_read_b64 v[88:89], v139 offset:8192
	v_lshl_add_u32 v92, v146, 11, v138
	v_add_u32_e32 v128, 16, v92
	v_lshl_add_u64 v[90:91], v[128:129], 2, s[4:5]
	s_waitcnt lgkmcnt(0)
	v_sub_f32_e32 v61, v61, v88
	v_sub_f32_e32 v60, v60, v88
	v_sub_f32_e32 v63, v63, v88
	v_sub_f32_e32 v62, v62, v88
	v_pk_mul_f32 v[62:63], v[88:89], v[62:63] op_sel:[1,0]
	v_pk_mul_f32 v[60:61], v[88:89], v[60:61] op_sel:[1,0]
	v_lshl_add_u64 v[88:89], v[128:129], 1, s[6:7]
	v_add_u32_e32 v128, 0x8010, v92
	s_waitcnt vmcnt(0)
	v_pk_fma_f32 v[60:61], v[80:81], v[60:61], v[84:85]
	v_pk_fma_f32 v[62:63], v[82:83], v[62:63], v[86:87]
	v_cndmask_b32_e32 v61, v147, v61, vcc
	v_cndmask_b32_e32 v63, v147, v63, vcc
	v_cndmask_b32_e32 v62, v147, v62, vcc
	v_cndmask_b32_e32 v60, v147, v60, vcc
	global_store_dwordx4 v[90:91], v[60:63], off nt
	v_lshl_add_u64 v[90:91], v[128:129], 2, s[4:5]
	s_nop 0
	v_cvt_pk_bf16_f32 v60, v60, v61
	v_cvt_pk_bf16_f32 v61, v62, v63
	ds_read_b64 v[62:63], v139 offset:8320
	global_store_dwordx2 v[88:89], v[60:61], off
	v_lshl_add_u64 v[60:61], v[128:129], 1, s[6:7]
	v_add_u32_e32 v128, 0x10010, v92
	s_waitcnt lgkmcnt(0)
	v_sub_f32_e32 v57, v57, v62
	v_sub_f32_e32 v56, v56, v62
	v_sub_f32_e32 v59, v59, v62
	v_sub_f32_e32 v58, v58, v62
	v_pk_mul_f32 v[58:59], v[62:63], v[58:59] op_sel:[1,0]
	v_pk_mul_f32 v[56:57], v[62:63], v[56:57] op_sel:[1,0]
	v_pk_fma_f32 v[58:59], v[82:83], v[58:59], v[86:87]
	v_pk_fma_f32 v[56:57], v[80:81], v[56:57], v[84:85]
	v_cndmask_b32_e32 v59, v147, v59, vcc
	v_cndmask_b32_e32 v58, v147, v58, vcc
	v_cndmask_b32_e32 v57, v147, v57, vcc
	v_cndmask_b32_e32 v56, v147, v56, vcc
	global_store_dwordx4 v[90:91], v[56:59], off nt
	v_lshl_add_u64 v[62:63], v[128:129], 2, s[4:5]
	s_nop 0
	v_cvt_pk_bf16_f32 v56, v56, v57
	v_cvt_pk_bf16_f32 v57, v58, v59
	ds_read_b64 v[58:59], v139 offset:8448
	global_store_dwordx2 v[60:61], v[56:57], off
	v_lshl_add_u64 v[56:57], v[128:129], 1, s[6:7]
	v_add_u32_e32 v128, 0x18010, v92
	s_waitcnt lgkmcnt(0)
	v_sub_f32_e32 v53, v53, v58
	v_sub_f32_e32 v52, v52, v58
	v_sub_f32_e32 v55, v55, v58
	v_sub_f32_e32 v54, v54, v58
	v_pk_mul_f32 v[54:55], v[58:59], v[54:55] op_sel:[1,0]
	v_pk_mul_f32 v[52:53], v[58:59], v[52:53] op_sel:[1,0]
	v_pk_fma_f32 v[54:55], v[82:83], v[54:55], v[86:87]
	v_pk_fma_f32 v[52:53], v[80:81], v[52:53], v[84:85]
	v_cndmask_b32_e32 v55, v147, v55, vcc
	v_cndmask_b32_e32 v54, v147, v54, vcc
	v_cndmask_b32_e32 v53, v147, v53, vcc
	v_cndmask_b32_e32 v52, v147, v52, vcc
	global_store_dwordx4 v[62:63], v[52:55], off nt
	s_nop 1
	v_cvt_pk_bf16_f32 v52, v52, v53
	v_cvt_pk_bf16_f32 v53, v54, v55
	ds_read_b64 v[54:55], v139 offset:8576
	global_store_dwordx2 v[56:57], v[52:53], off
	v_lshl_add_u64 v[52:53], v[128:129], 2, s[4:5]
	s_waitcnt lgkmcnt(0)
	v_sub_f32_e32 v49, v49, v54
	v_sub_f32_e32 v48, v48, v54
	v_sub_f32_e32 v51, v51, v54
	v_sub_f32_e32 v50, v50, v54
	v_pk_mul_f32 v[50:51], v[54:55], v[50:51] op_sel:[1,0]
	v_pk_mul_f32 v[48:49], v[54:55], v[48:49] op_sel:[1,0]
	v_pk_fma_f32 v[50:51], v[82:83], v[50:51], v[86:87]
	v_pk_fma_f32 v[48:49], v[80:81], v[48:49], v[84:85]
	v_cndmask_b32_e32 v51, v147, v51, vcc
	v_cndmask_b32_e32 v50, v147, v50, vcc
	v_cndmask_b32_e32 v49, v147, v49, vcc
	v_cndmask_b32_e32 v48, v147, v48, vcc
	global_store_dwordx4 v[52:53], v[48:51], off nt
	v_lshl_add_u64 v[52:53], v[128:129], 1, s[6:7]
	v_add_u32_e32 v128, 0x40010, v92
	v_cvt_pk_bf16_f32 v48, v48, v49
	v_cvt_pk_bf16_f32 v49, v50, v51
	ds_read_b64 v[50:51], v139 offset:9216
	global_store_dwordx2 v[52:53], v[48:49], off
	s_waitcnt lgkmcnt(0)
	v_sub_f32_e32 v49, v109, v50
	v_sub_f32_e32 v48, v108, v50
	v_sub_f32_e32 v53, v111, v50
	v_sub_f32_e32 v52, v110, v50
	v_pk_mul_f32 v[52:53], v[50:51], v[52:53] op_sel:[1,0]
	v_pk_mul_f32 v[48:49], v[50:51], v[48:49] op_sel:[1,0]
	v_pk_fma_f32 v[50:51], v[82:83], v[52:53], v[86:87]
	v_pk_fma_f32 v[48:49], v[80:81], v[48:49], v[84:85]
	v_cndmask_b32_e32 v51, v147, v51, vcc
	v_cndmask_b32_e32 v50, v147, v50, vcc
	v_cndmask_b32_e32 v49, v147, v49, vcc
	v_cndmask_b32_e32 v48, v147, v48, vcc
	v_lshl_add_u64 v[52:53], v[128:129], 2, s[4:5]
	global_store_dwordx4 v[52:53], v[48:51], off nt
	v_lshl_add_u64 v[52:53], v[128:129], 1, s[6:7]
	v_add_u32_e32 v128, 0x48010, v92
	v_cvt_pk_bf16_f32 v48, v48, v49
	v_cvt_pk_bf16_f32 v49, v50, v51
	ds_read_b64 v[50:51], v139 offset:9344
	global_store_dwordx2 v[52:53], v[48:49], off
	s_waitcnt lgkmcnt(0)
	v_sub_f32_e32 v49, v105, v50
	v_sub_f32_e32 v48, v104, v50
	v_sub_f32_e32 v53, v107, v50
	v_sub_f32_e32 v52, v106, v50
	v_pk_mul_f32 v[52:53], v[50:51], v[52:53] op_sel:[1,0]
	v_pk_mul_f32 v[48:49], v[50:51], v[48:49] op_sel:[1,0]
	v_pk_fma_f32 v[50:51], v[82:83], v[52:53], v[86:87]
	v_pk_fma_f32 v[48:49], v[80:81], v[48:49], v[84:85]
	v_cndmask_b32_e32 v51, v147, v51, vcc
	v_cndmask_b32_e32 v50, v147, v50, vcc
	v_cndmask_b32_e32 v49, v147, v49, vcc
	v_cndmask_b32_e32 v48, v147, v48, vcc
	v_lshl_add_u64 v[52:53], v[128:129], 2, s[4:5]
	global_store_dwordx4 v[52:53], v[48:51], off nt
	v_lshl_add_u64 v[52:53], v[128:129], 1, s[6:7]
	v_add_u32_e32 v128, 0x50010, v92
	v_cvt_pk_bf16_f32 v48, v48, v49
	v_cvt_pk_bf16_f32 v49, v50, v51
	ds_read_b64 v[50:51], v139 offset:9472
	global_store_dwordx2 v[52:53], v[48:49], off
	s_waitcnt lgkmcnt(0)
	v_sub_f32_e32 v49, v101, v50
	v_sub_f32_e32 v48, v100, v50
	v_sub_f32_e32 v53, v103, v50
	v_sub_f32_e32 v52, v102, v50
	v_pk_mul_f32 v[52:53], v[50:51], v[52:53] op_sel:[1,0]
	v_pk_mul_f32 v[48:49], v[50:51], v[48:49] op_sel:[1,0]
	v_pk_fma_f32 v[50:51], v[82:83], v[52:53], v[86:87]
	v_pk_fma_f32 v[48:49], v[80:81], v[48:49], v[84:85]
	v_cndmask_b32_e32 v51, v147, v51, vcc
	v_cndmask_b32_e32 v50, v147, v50, vcc
	v_cndmask_b32_e32 v49, v147, v49, vcc
	v_cndmask_b32_e32 v48, v147, v48, vcc
	v_lshl_add_u64 v[52:53], v[128:129], 2, s[4:5]
	global_store_dwordx4 v[52:53], v[48:51], off nt
	v_lshl_add_u64 v[52:53], v[128:129], 1, s[6:7]
	v_add_u32_e32 v128, 0x58010, v92
	v_cvt_pk_bf16_f32 v48, v48, v49
	v_cvt_pk_bf16_f32 v49, v50, v51
	ds_read_b64 v[50:51], v139 offset:9600
	global_store_dwordx2 v[52:53], v[48:49], off
	s_waitcnt lgkmcnt(0)
	v_sub_f32_e32 v49, v97, v50
	v_sub_f32_e32 v48, v96, v50
	v_sub_f32_e32 v53, v99, v50
	v_sub_f32_e32 v52, v98, v50
	v_pk_mul_f32 v[52:53], v[50:51], v[52:53] op_sel:[1,0]
	v_pk_mul_f32 v[48:49], v[50:51], v[48:49] op_sel:[1,0]
	v_pk_fma_f32 v[50:51], v[82:83], v[52:53], v[86:87]
	v_pk_fma_f32 v[48:49], v[80:81], v[48:49], v[84:85]
	v_cndmask_b32_e32 v51, v147, v51, vcc
	v_cndmask_b32_e32 v50, v147, v50, vcc
	v_cndmask_b32_e32 v49, v147, v49, vcc
	v_cndmask_b32_e32 v48, v147, v48, vcc
	v_lshl_add_u64 v[52:53], v[128:129], 2, s[4:5]
	global_store_dwordx4 v[52:53], v[48:51], off nt
	s_nop 1
	v_cvt_pk_bf16_f32 v48, v48, v49
	v_cvt_pk_bf16_f32 v49, v50, v51
	v_lshl_add_u64 v[50:51], v[128:129], 1, s[6:7]
	global_store_dwordx2 v[50:51], v[48:49], off
	global_load_dwordx4 v[48:51], v[140:141], off offset:512
	global_load_dwordx4 v[52:55], v[142:143], off offset:512
	ds_read_b64 v[56:57], v139 offset:8192
	v_lshl_add_u32 v60, v146, 11, v138
	v_add_u32_e32 v128, 0x80, v60
	v_lshl_add_u64 v[58:59], v[128:129], 2, s[4:5]
	s_waitcnt lgkmcnt(0)
	v_sub_f32_e32 v29, v29, v56
	v_sub_f32_e32 v28, v28, v56
	v_sub_f32_e32 v31, v31, v56
	v_sub_f32_e32 v30, v30, v56
	v_pk_mul_f32 v[30:31], v[56:57], v[30:31] op_sel:[1,0]
	v_pk_mul_f32 v[28:29], v[56:57], v[28:29] op_sel:[1,0]
	v_lshl_add_u64 v[56:57], v[128:129], 1, s[6:7]
	v_add_u32_e32 v128, 0x8080, v60
	s_waitcnt vmcnt(0)
	v_pk_fma_f32 v[28:29], v[48:49], v[28:29], v[52:53]
	v_pk_fma_f32 v[30:31], v[50:51], v[30:31], v[54:55]
	v_cndmask_b32_e32 v29, v147, v29, vcc
	v_cndmask_b32_e32 v31, v147, v31, vcc
	v_cndmask_b32_e32 v30, v147, v30, vcc
	v_cndmask_b32_e32 v28, v147, v28, vcc
	global_store_dwordx4 v[58:59], v[28:31], off nt
	v_lshl_add_u64 v[58:59], v[128:129], 2, s[4:5]
	s_nop 0
	v_cvt_pk_bf16_f32 v28, v28, v29
	v_cvt_pk_bf16_f32 v29, v30, v31
	ds_read_b64 v[30:31], v139 offset:8320
	global_store_dwordx2 v[56:57], v[28:29], off
	v_lshl_add_u64 v[28:29], v[128:129], 1, s[6:7]
	v_add_u32_e32 v128, 0x10080, v60
	s_waitcnt lgkmcnt(0)
	v_sub_f32_e32 v25, v25, v30
	v_sub_f32_e32 v24, v24, v30
	v_sub_f32_e32 v27, v27, v30
	v_sub_f32_e32 v26, v26, v30
	v_pk_mul_f32 v[26:27], v[30:31], v[26:27] op_sel:[1,0]
	v_pk_mul_f32 v[24:25], v[30:31], v[24:25] op_sel:[1,0]
	v_pk_fma_f32 v[26:27], v[50:51], v[26:27], v[54:55]
	v_pk_fma_f32 v[24:25], v[48:49], v[24:25], v[52:53]
	v_cndmask_b32_e32 v27, v147, v27, vcc
	v_cndmask_b32_e32 v26, v147, v26, vcc
	v_cndmask_b32_e32 v25, v147, v25, vcc
	v_cndmask_b32_e32 v24, v147, v24, vcc
	global_store_dwordx4 v[58:59], v[24:27], off nt
	s_nop 1
	v_cvt_pk_bf16_f32 v24, v24, v25
	v_cvt_pk_bf16_f32 v25, v26, v27
	ds_read_b64 v[26:27], v139 offset:8448
	global_store_dwordx2 v[28:29], v[24:25], off
	v_lshl_add_u64 v[24:25], v[128:129], 2, s[4:5]
	s_waitcnt lgkmcnt(0)
	v_sub_f32_e32 v21, v21, v26
	v_sub_f32_e32 v20, v20, v26
	v_sub_f32_e32 v23, v23, v26
	v_sub_f32_e32 v22, v22, v26
	v_pk_mul_f32 v[22:23], v[26:27], v[22:23] op_sel:[1,0]
	v_pk_mul_f32 v[20:21], v[26:27], v[20:21] op_sel:[1,0]
	v_pk_fma_f32 v[22:23], v[50:51], v[22:23], v[54:55]
	v_pk_fma_f32 v[20:21], v[48:49], v[20:21], v[52:53]
	v_cndmask_b32_e32 v23, v147, v23, vcc
	v_cndmask_b32_e32 v22, v147, v22, vcc
	v_cndmask_b32_e32 v21, v147, v21, vcc
	v_cndmask_b32_e32 v20, v147, v20, vcc
	global_store_dwordx4 v[24:25], v[20:23], off nt
	v_lshl_add_u64 v[24:25], v[128:129], 1, s[6:7]
	v_add_u32_e32 v128, 0x18080, v60
	v_cvt_pk_bf16_f32 v20, v20, v21
	v_cvt_pk_bf16_f32 v21, v22, v23
	ds_read_b64 v[22:23], v139 offset:8576
	global_store_dwordx2 v[24:25], v[20:21], off
	v_lshl_add_u64 v[20:21], v[128:129], 2, s[4:5]
	s_waitcnt lgkmcnt(0)
	v_sub_f32_e32 v17, v17, v22
	v_sub_f32_e32 v16, v16, v22
	v_sub_f32_e32 v19, v19, v22
	v_sub_f32_e32 v18, v18, v22
	v_pk_mul_f32 v[18:19], v[22:23], v[18:19] op_sel:[1,0]
	v_pk_mul_f32 v[16:17], v[22:23], v[16:17] op_sel:[1,0]
	v_pk_fma_f32 v[18:19], v[50:51], v[18:19], v[54:55]
	v_pk_fma_f32 v[16:17], v[48:49], v[16:17], v[52:53]
	v_cndmask_b32_e32 v19, v147, v19, vcc
	v_cndmask_b32_e32 v18, v147, v18, vcc
	v_cndmask_b32_e32 v17, v147, v17, vcc
	v_cndmask_b32_e32 v16, v147, v16, vcc
	global_store_dwordx4 v[20:21], v[16:19], off nt
	v_lshl_add_u64 v[20:21], v[128:129], 1, s[6:7]
	v_add_u32_e32 v128, 0x40080, v60
	v_cvt_pk_bf16_f32 v16, v16, v17
	v_cvt_pk_bf16_f32 v17, v18, v19
	ds_read_b64 v[18:19], v139 offset:9216
	global_store_dwordx2 v[20:21], v[16:17], off
	s_waitcnt lgkmcnt(0)
	v_sub_f32_e32 v17, v77, v18
	v_sub_f32_e32 v16, v76, v18
	v_sub_f32_e32 v21, v79, v18
	v_sub_f32_e32 v20, v78, v18
	v_pk_mul_f32 v[20:21], v[18:19], v[20:21] op_sel:[1,0]
	v_pk_mul_f32 v[16:17], v[18:19], v[16:17] op_sel:[1,0]
	v_pk_fma_f32 v[18:19], v[50:51], v[20:21], v[54:55]
	v_pk_fma_f32 v[16:17], v[48:49], v[16:17], v[52:53]
	v_cndmask_b32_e32 v19, v147, v19, vcc
	v_cndmask_b32_e32 v18, v147, v18, vcc
	v_cndmask_b32_e32 v17, v147, v17, vcc
	v_cndmask_b32_e32 v16, v147, v16, vcc
	v_lshl_add_u64 v[20:21], v[128:129], 2, s[4:5]
	global_store_dwordx4 v[20:21], v[16:19], off nt
	v_lshl_add_u64 v[20:21], v[128:129], 1, s[6:7]
	v_add_u32_e32 v128, 0x48080, v60
	v_cvt_pk_bf16_f32 v16, v16, v17
	v_cvt_pk_bf16_f32 v17, v18, v19
	ds_read_b64 v[18:19], v139 offset:9344
	global_store_dwordx2 v[20:21], v[16:17], off
	s_waitcnt lgkmcnt(0)
	v_sub_f32_e32 v17, v73, v18
	v_sub_f32_e32 v16, v72, v18
	v_sub_f32_e32 v21, v75, v18
	v_sub_f32_e32 v20, v74, v18
	v_pk_mul_f32 v[20:21], v[18:19], v[20:21] op_sel:[1,0]
	v_pk_mul_f32 v[16:17], v[18:19], v[16:17] op_sel:[1,0]
	v_pk_fma_f32 v[18:19], v[50:51], v[20:21], v[54:55]
	v_pk_fma_f32 v[16:17], v[48:49], v[16:17], v[52:53]
	v_cndmask_b32_e32 v19, v147, v19, vcc
	v_cndmask_b32_e32 v18, v147, v18, vcc
	v_cndmask_b32_e32 v17, v147, v17, vcc
	v_cndmask_b32_e32 v16, v147, v16, vcc
	v_lshl_add_u64 v[20:21], v[128:129], 2, s[4:5]
	global_store_dwordx4 v[20:21], v[16:19], off nt
	v_lshl_add_u64 v[20:21], v[128:129], 1, s[6:7]
	v_add_u32_e32 v128, 0x50080, v60
	v_cvt_pk_bf16_f32 v16, v16, v17
	v_cvt_pk_bf16_f32 v17, v18, v19
	ds_read_b64 v[18:19], v139 offset:9472
	global_store_dwordx2 v[20:21], v[16:17], off
	s_waitcnt lgkmcnt(0)
	v_sub_f32_e32 v17, v69, v18
	v_sub_f32_e32 v16, v68, v18
	v_sub_f32_e32 v21, v71, v18
	v_sub_f32_e32 v20, v70, v18
	v_pk_mul_f32 v[20:21], v[18:19], v[20:21] op_sel:[1,0]
	v_pk_mul_f32 v[16:17], v[18:19], v[16:17] op_sel:[1,0]
	v_pk_fma_f32 v[18:19], v[50:51], v[20:21], v[54:55]
	v_pk_fma_f32 v[16:17], v[48:49], v[16:17], v[52:53]
	v_cndmask_b32_e32 v19, v147, v19, vcc
	v_cndmask_b32_e32 v18, v147, v18, vcc
	v_cndmask_b32_e32 v17, v147, v17, vcc
	v_cndmask_b32_e32 v16, v147, v16, vcc
	v_lshl_add_u64 v[20:21], v[128:129], 2, s[4:5]
	global_store_dwordx4 v[20:21], v[16:19], off nt
	v_lshl_add_u64 v[20:21], v[128:129], 1, s[6:7]
	v_add_u32_e32 v128, 0x58080, v60
	v_cvt_pk_bf16_f32 v16, v16, v17
	v_cvt_pk_bf16_f32 v17, v18, v19
	ds_read_b64 v[18:19], v139 offset:9600
	global_store_dwordx2 v[20:21], v[16:17], off
	s_waitcnt lgkmcnt(0)
	v_sub_f32_e32 v17, v65, v18
	v_sub_f32_e32 v16, v64, v18
	v_sub_f32_e32 v21, v67, v18
	v_sub_f32_e32 v20, v66, v18
	v_pk_mul_f32 v[20:21], v[18:19], v[20:21] op_sel:[1,0]
	v_pk_mul_f32 v[16:17], v[18:19], v[16:17] op_sel:[1,0]
	v_pk_fma_f32 v[18:19], v[50:51], v[20:21], v[54:55]
	v_pk_fma_f32 v[16:17], v[48:49], v[16:17], v[52:53]
	v_cndmask_b32_e32 v19, v147, v19, vcc
	v_cndmask_b32_e32 v18, v147, v18, vcc
	v_cndmask_b32_e32 v17, v147, v17, vcc
	v_cndmask_b32_e32 v16, v147, v16, vcc
	v_lshl_add_u64 v[20:21], v[128:129], 2, s[4:5]
	global_store_dwordx4 v[20:21], v[16:19], off nt
	s_nop 1
	v_cvt_pk_bf16_f32 v16, v16, v17
	v_cvt_pk_bf16_f32 v17, v18, v19
	v_lshl_add_u64 v[18:19], v[128:129], 1, s[6:7]
	global_store_dwordx2 v[18:19], v[16:17], off
	global_load_dwordx4 v[16:19], v[140:141], off offset:576
	global_load_dwordx4 v[20:23], v[142:143], off offset:576
	ds_read_b64 v[24:25], v139 offset:8192
	v_lshl_add_u32 v26, v146, 11, v138
	v_add_u32_e32 v128, 0x90, v26
	s_waitcnt lgkmcnt(0)
	v_sub_f32_e32 v13, v13, v24
	v_sub_f32_e32 v12, v12, v24
	v_sub_f32_e32 v15, v15, v24
	v_sub_f32_e32 v14, v14, v24
	v_pk_mul_f32 v[14:15], v[24:25], v[14:15] op_sel:[1,0]
	v_pk_mul_f32 v[12:13], v[24:25], v[12:13] op_sel:[1,0]
	v_lshl_add_u64 v[24:25], v[128:129], 2, s[4:5]
	s_waitcnt vmcnt(0)
	v_pk_fma_f32 v[12:13], v[16:17], v[12:13], v[20:21]
	v_pk_fma_f32 v[14:15], v[18:19], v[14:15], v[22:23]
	v_cndmask_b32_e32 v13, v147, v13, vcc
	v_cndmask_b32_e32 v15, v147, v15, vcc
	v_cndmask_b32_e32 v14, v147, v14, vcc
	v_cndmask_b32_e32 v12, v147, v12, vcc
	global_store_dwordx4 v[24:25], v[12:15], off nt
	v_lshl_add_u64 v[24:25], v[128:129], 1, s[6:7]
	v_add_u32_e32 v128, 0x8090, v26
	v_cvt_pk_bf16_f32 v12, v12, v13
	v_cvt_pk_bf16_f32 v13, v14, v15
	ds_read_b64 v[14:15], v139 offset:8320
	global_store_dwordx2 v[24:25], v[12:13], off
	v_lshl_add_u64 v[12:13], v[128:129], 2, s[4:5]
	s_waitcnt lgkmcnt(0)
	v_sub_f32_e32 v9, v9, v14
	v_sub_f32_e32 v8, v8, v14
	v_sub_f32_e32 v11, v11, v14
	v_sub_f32_e32 v10, v10, v14
	v_pk_mul_f32 v[10:11], v[14:15], v[10:11] op_sel:[1,0]
	v_pk_mul_f32 v[8:9], v[14:15], v[8:9] op_sel:[1,0]
	v_pk_fma_f32 v[10:11], v[18:19], v[10:11], v[22:23]
	v_pk_fma_f32 v[8:9], v[16:17], v[8:9], v[20:21]
	v_cndmask_b32_e32 v11, v147, v11, vcc
	v_cndmask_b32_e32 v10, v147, v10, vcc
	v_cndmask_b32_e32 v9, v147, v9, vcc
	v_cndmask_b32_e32 v8, v147, v8, vcc
	global_store_dwordx4 v[12:13], v[8:11], off nt
	v_lshl_add_u64 v[12:13], v[128:129], 1, s[6:7]
	v_add_u32_e32 v128, 0x10090, v26
	v_cvt_pk_bf16_f32 v8, v8, v9
	v_cvt_pk_bf16_f32 v9, v10, v11
	ds_read_b64 v[10:11], v139 offset:8448
	global_store_dwordx2 v[12:13], v[8:9], off
	v_lshl_add_u64 v[8:9], v[128:129], 2, s[4:5]
	s_waitcnt lgkmcnt(0)
	v_sub_f32_e32 v5, v5, v10
	v_sub_f32_e32 v4, v4, v10
	v_sub_f32_e32 v7, v7, v10
	v_sub_f32_e32 v6, v6, v10
	v_pk_mul_f32 v[6:7], v[10:11], v[6:7] op_sel:[1,0]
	v_pk_mul_f32 v[4:5], v[10:11], v[4:5] op_sel:[1,0]
	v_pk_fma_f32 v[6:7], v[18:19], v[6:7], v[22:23]
	v_pk_fma_f32 v[4:5], v[16:17], v[4:5], v[20:21]
	v_cndmask_b32_e32 v7, v147, v7, vcc
	v_cndmask_b32_e32 v6, v147, v6, vcc
	v_cndmask_b32_e32 v5, v147, v5, vcc
	v_cndmask_b32_e32 v4, v147, v4, vcc
	global_store_dwordx4 v[8:9], v[4:7], off nt
	v_lshl_add_u64 v[8:9], v[128:129], 1, s[6:7]
	v_add_u32_e32 v128, 0x18090, v26
	v_cvt_pk_bf16_f32 v4, v4, v5
	v_cvt_pk_bf16_f32 v5, v6, v7
	ds_read_b64 v[6:7], v139 offset:8576
	global_store_dwordx2 v[8:9], v[4:5], off
	v_lshl_add_u64 v[4:5], v[128:129], 2, s[4:5]
	s_waitcnt lgkmcnt(0)
	v_sub_f32_e32 v1, v1, v6
	v_sub_f32_e32 v0, v0, v6
	v_sub_f32_e32 v3, v3, v6
	v_sub_f32_e32 v2, v2, v6
	v_pk_mul_f32 v[2:3], v[6:7], v[2:3] op_sel:[1,0]
	v_pk_mul_f32 v[0:1], v[6:7], v[0:1] op_sel:[1,0]
	v_pk_fma_f32 v[2:3], v[18:19], v[2:3], v[22:23]
	v_pk_fma_f32 v[0:1], v[16:17], v[0:1], v[20:21]
	v_cndmask_b32_e32 v3, v147, v3, vcc
	v_cndmask_b32_e32 v2, v147, v2, vcc
	v_cndmask_b32_e32 v1, v147, v1, vcc
	v_cndmask_b32_e32 v0, v147, v0, vcc
	global_store_dwordx4 v[4:5], v[0:3], off nt
	v_lshl_add_u64 v[4:5], v[128:129], 1, s[6:7]
	v_add_u32_e32 v128, 0x40090, v26
	v_cvt_pk_bf16_f32 v0, v0, v1
	v_cvt_pk_bf16_f32 v1, v2, v3
	ds_read_b64 v[2:3], v139 offset:9216
	global_store_dwordx2 v[4:5], v[0:1], off
	s_waitcnt lgkmcnt(0)
	v_sub_f32_e32 v1, v45, v2
	v_sub_f32_e32 v0, v44, v2
	v_sub_f32_e32 v5, v47, v2
	v_sub_f32_e32 v4, v46, v2
	v_pk_mul_f32 v[4:5], v[2:3], v[4:5] op_sel:[1,0]
	v_pk_mul_f32 v[0:1], v[2:3], v[0:1] op_sel:[1,0]
	v_pk_fma_f32 v[2:3], v[18:19], v[4:5], v[22:23]
	v_pk_fma_f32 v[0:1], v[16:17], v[0:1], v[20:21]
	v_cndmask_b32_e32 v3, v147, v3, vcc
	v_cndmask_b32_e32 v2, v147, v2, vcc
	v_cndmask_b32_e32 v1, v147, v1, vcc
	v_cndmask_b32_e32 v0, v147, v0, vcc
	v_lshl_add_u64 v[4:5], v[128:129], 2, s[4:5]
	global_store_dwordx4 v[4:5], v[0:3], off nt
	v_lshl_add_u64 v[4:5], v[128:129], 1, s[6:7]
	v_add_u32_e32 v128, 0x48090, v26
	v_cvt_pk_bf16_f32 v0, v0, v1
	v_cvt_pk_bf16_f32 v1, v2, v3
	ds_read_b64 v[2:3], v139 offset:9344
	global_store_dwordx2 v[4:5], v[0:1], off
	s_waitcnt lgkmcnt(0)
	v_sub_f32_e32 v1, v41, v2
	v_sub_f32_e32 v0, v40, v2
	v_sub_f32_e32 v5, v43, v2
	v_sub_f32_e32 v4, v42, v2
	v_pk_mul_f32 v[4:5], v[2:3], v[4:5] op_sel:[1,0]
	v_pk_mul_f32 v[0:1], v[2:3], v[0:1] op_sel:[1,0]
	v_pk_fma_f32 v[2:3], v[18:19], v[4:5], v[22:23]
	v_pk_fma_f32 v[0:1], v[16:17], v[0:1], v[20:21]
	v_cndmask_b32_e32 v3, v147, v3, vcc
	v_cndmask_b32_e32 v2, v147, v2, vcc
	v_cndmask_b32_e32 v1, v147, v1, vcc
	v_cndmask_b32_e32 v0, v147, v0, vcc
	v_lshl_add_u64 v[4:5], v[128:129], 2, s[4:5]
	global_store_dwordx4 v[4:5], v[0:3], off nt
	v_lshl_add_u64 v[4:5], v[128:129], 1, s[6:7]
	v_add_u32_e32 v128, 0x50090, v26
	v_cvt_pk_bf16_f32 v0, v0, v1
	v_cvt_pk_bf16_f32 v1, v2, v3
	ds_read_b64 v[2:3], v139 offset:9472
	global_store_dwordx2 v[4:5], v[0:1], off
	s_waitcnt lgkmcnt(0)
	v_sub_f32_e32 v1, v37, v2
	v_sub_f32_e32 v0, v36, v2
	v_sub_f32_e32 v5, v39, v2
	v_sub_f32_e32 v4, v38, v2
	v_pk_mul_f32 v[4:5], v[2:3], v[4:5] op_sel:[1,0]
	v_pk_mul_f32 v[0:1], v[2:3], v[0:1] op_sel:[1,0]
	v_pk_fma_f32 v[2:3], v[18:19], v[4:5], v[22:23]
	v_pk_fma_f32 v[0:1], v[16:17], v[0:1], v[20:21]
	v_cndmask_b32_e32 v3, v147, v3, vcc
	v_cndmask_b32_e32 v2, v147, v2, vcc
	v_cndmask_b32_e32 v1, v147, v1, vcc
	v_cndmask_b32_e32 v0, v147, v0, vcc
	v_lshl_add_u64 v[4:5], v[128:129], 2, s[4:5]
	global_store_dwordx4 v[4:5], v[0:3], off nt
	v_lshl_add_u64 v[4:5], v[128:129], 1, s[6:7]
	v_add_u32_e32 v128, 0x58090, v26
	v_cvt_pk_bf16_f32 v0, v0, v1
	v_cvt_pk_bf16_f32 v1, v2, v3
	ds_read_b64 v[2:3], v139 offset:9600
	global_store_dwordx2 v[4:5], v[0:1], off
	s_waitcnt lgkmcnt(0)
	v_sub_f32_e32 v1, v33, v2
	v_sub_f32_e32 v0, v32, v2
	v_sub_f32_e32 v5, v35, v2
	v_sub_f32_e32 v4, v34, v2
	v_pk_mul_f32 v[4:5], v[2:3], v[4:5] op_sel:[1,0]
	v_pk_mul_f32 v[0:1], v[2:3], v[0:1] op_sel:[1,0]
	v_pk_fma_f32 v[2:3], v[18:19], v[4:5], v[22:23]
	v_pk_fma_f32 v[0:1], v[16:17], v[0:1], v[20:21]
	v_cndmask_b32_e32 v3, v147, v3, vcc
	v_cndmask_b32_e32 v2, v147, v2, vcc
	v_cndmask_b32_e32 v1, v147, v1, vcc
	v_cndmask_b32_e32 v0, v147, v0, vcc
	v_lshl_add_u64 v[4:5], v[128:129], 2, s[4:5]
	global_store_dwordx4 v[4:5], v[0:3], off nt
	s_nop 1
	v_cvt_pk_bf16_f32 v0, v0, v1
	v_cvt_pk_bf16_f32 v1, v2, v3
	v_lshl_add_u64 v[2:3], v[128:129], 1, s[6:7]
	global_store_dwordx2 v[2:3], v[0:1], off

.LBB0_166:
	s_or_b64 exec, exec, s[6:7]
	v_readlane_b32 s4, v255, 7
	v_readlane_b32 s5, v255, 8
	s_lshl_b32 s4, s4, 11
	s_ashr_i32 s5, s4, 31
	v_readlane_b32 s36, v254, 35
	s_lshl_b64 s[4:5], s[4:5], 2
	v_readlane_b32 s38, v254, 37
	v_readlane_b32 s39, v254, 38
	s_add_u32 s6, s38, s4
	v_readlane_b32 s40, v254, 39
	s_addc_u32 s7, s39, s5
	v_readlane_b32 s41, v254, 40
	s_add_u32 s4, s40, s4
	v_mov_b32_e32 v139, v129
	s_addc_u32 s5, s41, s5
	v_lshlrev_b64 v[134:135], 2, v[138:139]
	v_lshl_add_u64 v[140:141], s[6:7], 0, v[134:135]
	v_lshl_add_u64 v[142:143], s[4:5], 0, v[134:135]
	s_waitcnt lgkmcnt(0)
	s_barrier
	global_load_dwordx4 v[130:133], v[140:141], off
	global_load_dwordx4 v[134:137], v[142:143], off
	s_lshl_b32 s4, s24, 3
	s_add_i32 s4, s4, 0
	v_lshl_add_u32 v139, v144, 3, s4
	ds_read_b64 v[152:153], v139 offset:8192
	s_waitcnt lgkmcnt(0)
	v_cmp_eq_u32_e32 vcc, 0, v128
	v_lshl_add_u32 v128, v146, 11, v138
	v_mov_b32_e32 v147, 0x7fc00000
	v_lshl_add_u64 v[156:157], v[128:129], 2, s[0:1]
	v_sub_f32_e32 v93, v93, v152
	v_sub_f32_e32 v92, v92, v152
	v_sub_f32_e32 v95, v95, v152
	v_sub_f32_e32 v94, v94, v152
	v_pk_mul_f32 v[94:95], v[152:153], v[94:95] op_sel:[1,0]
	v_pk_mul_f32 v[92:93], v[152:153], v[92:93] op_sel:[1,0]
	v_readlane_b32 s4, v255, 9
	v_mov_b32_e32 v145, v129
	v_readlane_b32 s5, v255, 10
	v_add_u32_e32 v144, 0x8000, v128
	v_mov_b32_e32 v149, v129
	v_lshl_add_u64 v[152:153], v[128:129], 1, s[4:5]
	v_add_u32_e32 v148, 0x10000, v128
	v_mov_b32_e32 v151, v129
	v_add_u32_e32 v150, 0x18000, v128
	v_mov_b32_e32 v155, v129
	v_add_u32_e32 v154, 0x40000, v128
	v_readlane_b32 s37, v254, 36
	v_readlane_b32 s42, v254, 41
	v_readlane_b32 s43, v254, 42
	v_readlane_b32 s44, v254, 43
	v_readlane_b32 s45, v254, 44
	v_readlane_b32 s46, v254, 45
	v_readlane_b32 s47, v254, 46
	v_readlane_b32 s48, v254, 47
	v_readlane_b32 s49, v254, 48
	v_readlane_b32 s50, v254, 49
	v_readlane_b32 s51, v254, 50
	s_waitcnt vmcnt(0)
	v_pk_fma_f32 v[92:93], v[130:131], v[92:93], v[134:135]
	v_pk_fma_f32 v[94:95], v[132:133], v[94:95], v[136:137]
	v_cndmask_b32_e32 v93, v147, v93, vcc
	v_cndmask_b32_e32 v95, v147, v95, vcc
	v_cndmask_b32_e32 v94, v147, v94, vcc
	v_cndmask_b32_e32 v92, v147, v92, vcc
	global_store_dwordx4 v[156:157], v[92:95], off nt
	v_lshl_add_u64 v[156:157], v[144:145], 2, s[0:1]
	s_nop 0
	v_cvt_pk_bf16_f32 v92, v92, v93
	v_cvt_pk_bf16_f32 v93, v94, v95
	ds_read_b64 v[94:95], v139 offset:8320
	global_store_dwordx2 v[152:153], v[92:93], off
	v_lshl_add_u64 v[92:93], v[144:145], 1, s[4:5]
	s_waitcnt lgkmcnt(0)
	v_sub_f32_e32 v89, v89, v94
	v_sub_f32_e32 v88, v88, v94
	v_sub_f32_e32 v91, v91, v94
	v_sub_f32_e32 v90, v90, v94
	v_pk_mul_f32 v[90:91], v[94:95], v[90:91] op_sel:[1,0]
	v_pk_mul_f32 v[88:89], v[94:95], v[88:89] op_sel:[1,0]
	v_pk_fma_f32 v[90:91], v[132:133], v[90:91], v[136:137]
	v_pk_fma_f32 v[88:89], v[130:131], v[88:89], v[134:135]
	v_cndmask_b32_e32 v91, v147, v91, vcc
	v_cndmask_b32_e32 v90, v147, v90, vcc
	v_cndmask_b32_e32 v89, v147, v89, vcc
	v_cndmask_b32_e32 v88, v147, v88, vcc
	global_store_dwordx4 v[156:157], v[88:91], off nt
	v_lshl_add_u64 v[94:95], v[148:149], 2, s[0:1]
	s_nop 0
	v_cvt_pk_bf16_f32 v88, v88, v89
	v_cvt_pk_bf16_f32 v89, v90, v91
	ds_read_b64 v[90:91], v139 offset:8448
	global_store_dwordx2 v[92:93], v[88:89], off
	v_lshl_add_u64 v[88:89], v[148:149], 1, s[4:5]
	s_waitcnt lgkmcnt(0)
	v_sub_f32_e32 v85, v85, v90
	v_sub_f32_e32 v84, v84, v90
	v_sub_f32_e32 v87, v87, v90
	v_sub_f32_e32 v86, v86, v90
	v_pk_mul_f32 v[86:87], v[90:91], v[86:87] op_sel:[1,0]
	v_pk_mul_f32 v[84:85], v[90:91], v[84:85] op_sel:[1,0]
	v_pk_fma_f32 v[86:87], v[132:133], v[86:87], v[136:137]
	v_pk_fma_f32 v[84:85], v[130:131], v[84:85], v[134:135]
	v_cndmask_b32_e32 v87, v147, v87, vcc
	v_cndmask_b32_e32 v86, v147, v86, vcc
	v_cndmask_b32_e32 v85, v147, v85, vcc
	v_cndmask_b32_e32 v84, v147, v84, vcc
	global_store_dwordx4 v[94:95], v[84:87], off nt
	v_lshl_add_u64 v[90:91], v[150:151], 2, s[0:1]
	s_nop 0
	v_cvt_pk_bf16_f32 v84, v84, v85
	v_cvt_pk_bf16_f32 v85, v86, v87
	ds_read_b64 v[86:87], v139 offset:8576
	global_store_dwordx2 v[88:89], v[84:85], off
	v_lshl_add_u64 v[84:85], v[150:151], 1, s[4:5]
	s_waitcnt lgkmcnt(0)
	v_sub_f32_e32 v81, v81, v86
	v_sub_f32_e32 v80, v80, v86
	v_sub_f32_e32 v83, v83, v86
	v_sub_f32_e32 v82, v82, v86
	v_pk_mul_f32 v[82:83], v[86:87], v[82:83] op_sel:[1,0]
	v_pk_mul_f32 v[80:81], v[86:87], v[80:81] op_sel:[1,0]
	v_pk_fma_f32 v[82:83], v[132:133], v[82:83], v[136:137]
	v_pk_fma_f32 v[80:81], v[130:131], v[80:81], v[134:135]
	v_cndmask_b32_e32 v83, v147, v83, vcc
	v_cndmask_b32_e32 v82, v147, v82, vcc
	v_cndmask_b32_e32 v81, v147, v81, vcc
	v_cndmask_b32_e32 v80, v147, v80, vcc
	global_store_dwordx4 v[90:91], v[80:83], off nt
	v_lshl_add_u64 v[86:87], v[154:155], 2, s[0:1]
	s_nop 0
	v_cvt_pk_bf16_f32 v80, v80, v81
	v_cvt_pk_bf16_f32 v81, v82, v83
	ds_read_b64 v[82:83], v139 offset:9216
	global_store_dwordx2 v[84:85], v[80:81], off
	s_waitcnt lgkmcnt(0)
	v_sub_f32_e32 v81, v125, v82
	v_sub_f32_e32 v80, v124, v82
	v_sub_f32_e32 v85, v127, v82
	v_sub_f32_e32 v84, v126, v82
	v_pk_mul_f32 v[84:85], v[82:83], v[84:85] op_sel:[1,0]
	v_pk_mul_f32 v[80:81], v[82:83], v[80:81] op_sel:[1,0]
	v_pk_fma_f32 v[82:83], v[132:133], v[84:85], v[136:137]
	v_pk_fma_f32 v[80:81], v[130:131], v[80:81], v[134:135]
	v_cndmask_b32_e32 v83, v147, v83, vcc
	v_cndmask_b32_e32 v82, v147, v82, vcc
	v_cndmask_b32_e32 v81, v147, v81, vcc
	v_cndmask_b32_e32 v80, v147, v80, vcc
	global_store_dwordx4 v[86:87], v[80:83], off nt
	v_lshl_add_u64 v[86:87], v[154:155], 1, s[4:5]
	v_add_u32_e32 v84, 0x48000, v128
	v_cvt_pk_bf16_f32 v80, v80, v81
	v_cvt_pk_bf16_f32 v81, v82, v83
	ds_read_b64 v[82:83], v139 offset:9344
	global_store_dwordx2 v[86:87], v[80:81], off
	v_mov_b32_e32 v85, v129
	s_waitcnt lgkmcnt(0)
	v_sub_f32_e32 v81, v121, v82
	v_sub_f32_e32 v80, v120, v82
	v_sub_f32_e32 v87, v123, v82
	v_sub_f32_e32 v86, v122, v82
	v_pk_mul_f32 v[86:87], v[82:83], v[86:87] op_sel:[1,0]
	v_pk_mul_f32 v[80:81], v[82:83], v[80:81] op_sel:[1,0]
	v_pk_fma_f32 v[82:83], v[132:133], v[86:87], v[136:137]
	v_pk_fma_f32 v[80:81], v[130:131], v[80:81], v[134:135]
	v_cndmask_b32_e32 v83, v147, v83, vcc
	v_cndmask_b32_e32 v82, v147, v82, vcc
	v_cndmask_b32_e32 v81, v147, v81, vcc
	v_cndmask_b32_e32 v80, v147, v80, vcc
	v_lshl_add_u64 v[86:87], v[84:85], 2, s[0:1]
	global_store_dwordx4 v[86:87], v[80:83], off nt
	v_lshl_add_u64 v[84:85], v[84:85], 1, s[4:5]
	s_nop 0
	v_cvt_pk_bf16_f32 v80, v80, v81
	v_cvt_pk_bf16_f32 v81, v82, v83
	ds_read_b64 v[82:83], v139 offset:9472
	global_store_dwordx2 v[84:85], v[80:81], off
	v_add_u32_e32 v84, 0x50000, v128
	v_mov_b32_e32 v85, v129
	v_add_u32_e32 v128, 0x58000, v128
	s_waitcnt lgkmcnt(0)
	v_sub_f32_e32 v81, v117, v82
	v_sub_f32_e32 v80, v116, v82
	v_sub_f32_e32 v87, v119, v82
	v_sub_f32_e32 v86, v118, v82
	v_pk_mul_f32 v[86:87], v[82:83], v[86:87] op_sel:[1,0]
	v_pk_mul_f32 v[80:81], v[82:83], v[80:81] op_sel:[1,0]
	v_pk_fma_f32 v[82:83], v[132:133], v[86:87], v[136:137]
	v_pk_fma_f32 v[80:81], v[130:131], v[80:81], v[134:135]
	v_cndmask_b32_e32 v83, v147, v83, vcc
	v_cndmask_b32_e32 v82, v147, v82, vcc
	v_cndmask_b32_e32 v81, v147, v81, vcc
	v_cndmask_b32_e32 v80, v147, v80, vcc
	v_lshl_add_u64 v[86:87], v[84:85], 2, s[0:1]
	global_store_dwordx4 v[86:87], v[80:83], off nt
	v_lshl_add_u64 v[84:85], v[84:85], 1, s[4:5]
	s_nop 0
	v_cvt_pk_bf16_f32 v80, v80, v81
	v_cvt_pk_bf16_f32 v81, v82, v83
	ds_read_b64 v[82:83], v139 offset:9600
	global_store_dwordx2 v[84:85], v[80:81], off
	s_waitcnt lgkmcnt(0)
	v_sub_f32_e32 v81, v113, v82
	v_sub_f32_e32 v80, v112, v82
	v_sub_f32_e32 v85, v115, v82
	v_sub_f32_e32 v84, v114, v82
	v_pk_mul_f32 v[84:85], v[82:83], v[84:85] op_sel:[1,0]
	v_pk_mul_f32 v[80:81], v[82:83], v[80:81] op_sel:[1,0]
	v_pk_fma_f32 v[82:83], v[132:133], v[84:85], v[136:137]
	v_pk_fma_f32 v[80:81], v[130:131], v[80:81], v[134:135]
	v_cndmask_b32_e32 v83, v147, v83, vcc
	v_cndmask_b32_e32 v82, v147, v82, vcc
	v_cndmask_b32_e32 v81, v147, v81, vcc
	v_cndmask_b32_e32 v80, v147, v80, vcc
	v_lshl_add_u64 v[84:85], v[128:129], 2, s[0:1]
	global_store_dwordx4 v[84:85], v[80:83], off nt
	s_nop 1
	v_cvt_pk_bf16_f32 v80, v80, v81
	v_cvt_pk_bf16_f32 v81, v82, v83
	v_lshl_add_u64 v[82:83], v[128:129], 1, s[4:5]
	global_store_dwordx2 v[82:83], v[80:81], off
	global_load_dwordx4 v[80:83], v[140:141], off offset:64
	global_load_dwordx4 v[84:87], v[142:143], off offset:64
	ds_read_b64 v[88:89], v139 offset:8192
	v_lshl_add_u32 v92, v146, 11, v138
	v_add_u32_e32 v128, 16, v92
	v_lshl_add_u64 v[90:91], v[128:129], 2, s[0:1]
	s_waitcnt lgkmcnt(0)
	v_sub_f32_e32 v61, v61, v88
	v_sub_f32_e32 v60, v60, v88
	v_sub_f32_e32 v63, v63, v88
	v_sub_f32_e32 v62, v62, v88
	v_pk_mul_f32 v[62:63], v[88:89], v[62:63] op_sel:[1,0]
	v_pk_mul_f32 v[60:61], v[88:89], v[60:61] op_sel:[1,0]
	v_lshl_add_u64 v[88:89], v[128:129], 1, s[4:5]
	v_add_u32_e32 v128, 0x8010, v92
	s_waitcnt vmcnt(0)
	v_pk_fma_f32 v[60:61], v[80:81], v[60:61], v[84:85]
	v_pk_fma_f32 v[62:63], v[82:83], v[62:63], v[86:87]
	v_cndmask_b32_e32 v61, v147, v61, vcc
	v_cndmask_b32_e32 v63, v147, v63, vcc
	v_cndmask_b32_e32 v62, v147, v62, vcc
	v_cndmask_b32_e32 v60, v147, v60, vcc
	global_store_dwordx4 v[90:91], v[60:63], off nt
	v_lshl_add_u64 v[90:91], v[128:129], 2, s[0:1]
	s_nop 0
	v_cvt_pk_bf16_f32 v60, v60, v61
	v_cvt_pk_bf16_f32 v61, v62, v63
	ds_read_b64 v[62:63], v139 offset:8320
	global_store_dwordx2 v[88:89], v[60:61], off
	v_lshl_add_u64 v[60:61], v[128:129], 1, s[4:5]
	v_add_u32_e32 v128, 0x10010, v92
	s_waitcnt lgkmcnt(0)
	v_sub_f32_e32 v57, v57, v62
	v_sub_f32_e32 v56, v56, v62
	v_sub_f32_e32 v59, v59, v62
	v_sub_f32_e32 v58, v58, v62
	v_pk_mul_f32 v[58:59], v[62:63], v[58:59] op_sel:[1,0]
	v_pk_mul_f32 v[56:57], v[62:63], v[56:57] op_sel:[1,0]
	v_pk_fma_f32 v[58:59], v[82:83], v[58:59], v[86:87]
	v_pk_fma_f32 v[56:57], v[80:81], v[56:57], v[84:85]
	v_cndmask_b32_e32 v59, v147, v59, vcc
	v_cndmask_b32_e32 v58, v147, v58, vcc
	v_cndmask_b32_e32 v57, v147, v57, vcc
	v_cndmask_b32_e32 v56, v147, v56, vcc
	global_store_dwordx4 v[90:91], v[56:59], off nt
	v_lshl_add_u64 v[62:63], v[128:129], 2, s[0:1]
	s_nop 0
	v_cvt_pk_bf16_f32 v56, v56, v57
	v_cvt_pk_bf16_f32 v57, v58, v59
	ds_read_b64 v[58:59], v139 offset:8448
	global_store_dwordx2 v[60:61], v[56:57], off
	v_lshl_add_u64 v[56:57], v[128:129], 1, s[4:5]
	v_add_u32_e32 v128, 0x18010, v92
	s_waitcnt lgkmcnt(0)
	v_sub_f32_e32 v53, v53, v58
	v_sub_f32_e32 v52, v52, v58
	v_sub_f32_e32 v55, v55, v58
	v_sub_f32_e32 v54, v54, v58
	v_pk_mul_f32 v[54:55], v[58:59], v[54:55] op_sel:[1,0]
	v_pk_mul_f32 v[52:53], v[58:59], v[52:53] op_sel:[1,0]
	v_pk_fma_f32 v[54:55], v[82:83], v[54:55], v[86:87]
	v_pk_fma_f32 v[52:53], v[80:81], v[52:53], v[84:85]
	v_cndmask_b32_e32 v55, v147, v55, vcc
	v_cndmask_b32_e32 v54, v147, v54, vcc
	v_cndmask_b32_e32 v53, v147, v53, vcc
	v_cndmask_b32_e32 v52, v147, v52, vcc
	global_store_dwordx4 v[62:63], v[52:55], off nt
	s_nop 1
	v_cvt_pk_bf16_f32 v52, v52, v53
	v_cvt_pk_bf16_f32 v53, v54, v55
	ds_read_b64 v[54:55], v139 offset:8576
	global_store_dwordx2 v[56:57], v[52:53], off
	v_lshl_add_u64 v[52:53], v[128:129], 2, s[0:1]
	s_waitcnt lgkmcnt(0)
	v_sub_f32_e32 v49, v49, v54
	v_sub_f32_e32 v48, v48, v54
	v_sub_f32_e32 v51, v51, v54
	v_sub_f32_e32 v50, v50, v54
	v_pk_mul_f32 v[50:51], v[54:55], v[50:51] op_sel:[1,0]
	v_pk_mul_f32 v[48:49], v[54:55], v[48:49] op_sel:[1,0]
	v_pk_fma_f32 v[50:51], v[82:83], v[50:51], v[86:87]
	v_pk_fma_f32 v[48:49], v[80:81], v[48:49], v[84:85]
	v_cndmask_b32_e32 v51, v147, v51, vcc
	v_cndmask_b32_e32 v50, v147, v50, vcc
	v_cndmask_b32_e32 v49, v147, v49, vcc
	v_cndmask_b32_e32 v48, v147, v48, vcc
	global_store_dwordx4 v[52:53], v[48:51], off nt
	v_lshl_add_u64 v[52:53], v[128:129], 1, s[4:5]
	v_add_u32_e32 v128, 0x40010, v92
	v_cvt_pk_bf16_f32 v48, v48, v49
	v_cvt_pk_bf16_f32 v49, v50, v51
	ds_read_b64 v[50:51], v139 offset:9216
	global_store_dwordx2 v[52:53], v[48:49], off
	s_waitcnt lgkmcnt(0)
	v_sub_f32_e32 v49, v109, v50
	v_sub_f32_e32 v48, v108, v50
	v_sub_f32_e32 v53, v111, v50
	v_sub_f32_e32 v52, v110, v50
	v_pk_mul_f32 v[52:53], v[50:51], v[52:53] op_sel:[1,0]
	v_pk_mul_f32 v[48:49], v[50:51], v[48:49] op_sel:[1,0]
	v_pk_fma_f32 v[50:51], v[82:83], v[52:53], v[86:87]
	v_pk_fma_f32 v[48:49], v[80:81], v[48:49], v[84:85]
	v_cndmask_b32_e32 v51, v147, v51, vcc
	v_cndmask_b32_e32 v50, v147, v50, vcc
	v_cndmask_b32_e32 v49, v147, v49, vcc
	v_cndmask_b32_e32 v48, v147, v48, vcc
	v_lshl_add_u64 v[52:53], v[128:129], 2, s[0:1]
	global_store_dwordx4 v[52:53], v[48:51], off nt
	v_lshl_add_u64 v[52:53], v[128:129], 1, s[4:5]
	v_add_u32_e32 v128, 0x48010, v92
	v_cvt_pk_bf16_f32 v48, v48, v49
	v_cvt_pk_bf16_f32 v49, v50, v51
	ds_read_b64 v[50:51], v139 offset:9344
	global_store_dwordx2 v[52:53], v[48:49], off
	s_waitcnt lgkmcnt(0)
	v_sub_f32_e32 v49, v105, v50
	v_sub_f32_e32 v48, v104, v50
	v_sub_f32_e32 v53, v107, v50
	v_sub_f32_e32 v52, v106, v50
	v_pk_mul_f32 v[52:53], v[50:51], v[52:53] op_sel:[1,0]
	v_pk_mul_f32 v[48:49], v[50:51], v[48:49] op_sel:[1,0]
	v_pk_fma_f32 v[50:51], v[82:83], v[52:53], v[86:87]
	v_pk_fma_f32 v[48:49], v[80:81], v[48:49], v[84:85]
	v_cndmask_b32_e32 v51, v147, v51, vcc
	v_cndmask_b32_e32 v50, v147, v50, vcc
	v_cndmask_b32_e32 v49, v147, v49, vcc
	v_cndmask_b32_e32 v48, v147, v48, vcc
	v_lshl_add_u64 v[52:53], v[128:129], 2, s[0:1]
	global_store_dwordx4 v[52:53], v[48:51], off nt
	v_lshl_add_u64 v[52:53], v[128:129], 1, s[4:5]
	v_add_u32_e32 v128, 0x50010, v92
	v_cvt_pk_bf16_f32 v48, v48, v49
	v_cvt_pk_bf16_f32 v49, v50, v51
	ds_read_b64 v[50:51], v139 offset:9472
	global_store_dwordx2 v[52:53], v[48:49], off
	s_waitcnt lgkmcnt(0)
	v_sub_f32_e32 v49, v101, v50
	v_sub_f32_e32 v48, v100, v50
	v_sub_f32_e32 v53, v103, v50
	v_sub_f32_e32 v52, v102, v50
	v_pk_mul_f32 v[52:53], v[50:51], v[52:53] op_sel:[1,0]
	v_pk_mul_f32 v[48:49], v[50:51], v[48:49] op_sel:[1,0]
	v_pk_fma_f32 v[50:51], v[82:83], v[52:53], v[86:87]
	v_pk_fma_f32 v[48:49], v[80:81], v[48:49], v[84:85]
	v_cndmask_b32_e32 v51, v147, v51, vcc
	v_cndmask_b32_e32 v50, v147, v50, vcc
	v_cndmask_b32_e32 v49, v147, v49, vcc
	v_cndmask_b32_e32 v48, v147, v48, vcc
	v_lshl_add_u64 v[52:53], v[128:129], 2, s[0:1]
	global_store_dwordx4 v[52:53], v[48:51], off nt
	v_lshl_add_u64 v[52:53], v[128:129], 1, s[4:5]
	v_add_u32_e32 v128, 0x58010, v92
	v_cvt_pk_bf16_f32 v48, v48, v49
	v_cvt_pk_bf16_f32 v49, v50, v51
	ds_read_b64 v[50:51], v139 offset:9600
	global_store_dwordx2 v[52:53], v[48:49], off
	s_waitcnt lgkmcnt(0)
	v_sub_f32_e32 v49, v97, v50
	v_sub_f32_e32 v48, v96, v50
	v_sub_f32_e32 v53, v99, v50
	v_sub_f32_e32 v52, v98, v50
	v_pk_mul_f32 v[52:53], v[50:51], v[52:53] op_sel:[1,0]
	v_pk_mul_f32 v[48:49], v[50:51], v[48:49] op_sel:[1,0]
	v_pk_fma_f32 v[50:51], v[82:83], v[52:53], v[86:87]
	v_pk_fma_f32 v[48:49], v[80:81], v[48:49], v[84:85]
	v_cndmask_b32_e32 v51, v147, v51, vcc
	v_cndmask_b32_e32 v50, v147, v50, vcc
	v_cndmask_b32_e32 v49, v147, v49, vcc
	v_cndmask_b32_e32 v48, v147, v48, vcc
	v_lshl_add_u64 v[52:53], v[128:129], 2, s[0:1]
	global_store_dwordx4 v[52:53], v[48:51], off nt
	s_nop 1
	v_cvt_pk_bf16_f32 v48, v48, v49
	v_cvt_pk_bf16_f32 v49, v50, v51
	v_lshl_add_u64 v[50:51], v[128:129], 1, s[4:5]
	global_store_dwordx2 v[50:51], v[48:49], off
	global_load_dwordx4 v[48:51], v[140:141], off offset:512
	global_load_dwordx4 v[52:55], v[142:143], off offset:512
	ds_read_b64 v[56:57], v139 offset:8192
	v_lshl_add_u32 v60, v146, 11, v138
	v_add_u32_e32 v128, 0x80, v60
	v_lshl_add_u64 v[58:59], v[128:129], 2, s[0:1]
	s_waitcnt lgkmcnt(0)
	v_sub_f32_e32 v29, v29, v56
	v_sub_f32_e32 v28, v28, v56
	v_sub_f32_e32 v31, v31, v56
	v_sub_f32_e32 v30, v30, v56
	v_pk_mul_f32 v[30:31], v[56:57], v[30:31] op_sel:[1,0]
	v_pk_mul_f32 v[28:29], v[56:57], v[28:29] op_sel:[1,0]
	v_lshl_add_u64 v[56:57], v[128:129], 1, s[4:5]
	v_add_u32_e32 v128, 0x8080, v60
	s_waitcnt vmcnt(0)
	v_pk_fma_f32 v[28:29], v[48:49], v[28:29], v[52:53]
	v_pk_fma_f32 v[30:31], v[50:51], v[30:31], v[54:55]
	v_cndmask_b32_e32 v29, v147, v29, vcc
	v_cndmask_b32_e32 v31, v147, v31, vcc
	v_cndmask_b32_e32 v30, v147, v30, vcc
	v_cndmask_b32_e32 v28, v147, v28, vcc
	global_store_dwordx4 v[58:59], v[28:31], off nt
	v_lshl_add_u64 v[58:59], v[128:129], 2, s[0:1]
	s_nop 0
	v_cvt_pk_bf16_f32 v28, v28, v29
	v_cvt_pk_bf16_f32 v29, v30, v31
	ds_read_b64 v[30:31], v139 offset:8320
	global_store_dwordx2 v[56:57], v[28:29], off
	v_lshl_add_u64 v[28:29], v[128:129], 1, s[4:5]
	v_add_u32_e32 v128, 0x10080, v60
	s_waitcnt lgkmcnt(0)
	v_sub_f32_e32 v25, v25, v30
	v_sub_f32_e32 v24, v24, v30
	v_sub_f32_e32 v27, v27, v30
	v_sub_f32_e32 v26, v26, v30
	v_pk_mul_f32 v[26:27], v[30:31], v[26:27] op_sel:[1,0]
	v_pk_mul_f32 v[24:25], v[30:31], v[24:25] op_sel:[1,0]
	v_pk_fma_f32 v[26:27], v[50:51], v[26:27], v[54:55]
	v_pk_fma_f32 v[24:25], v[48:49], v[24:25], v[52:53]
	v_cndmask_b32_e32 v27, v147, v27, vcc
	v_cndmask_b32_e32 v26, v147, v26, vcc
	v_cndmask_b32_e32 v25, v147, v25, vcc
	v_cndmask_b32_e32 v24, v147, v24, vcc
	global_store_dwordx4 v[58:59], v[24:27], off nt
	s_nop 1
	v_cvt_pk_bf16_f32 v24, v24, v25
	v_cvt_pk_bf16_f32 v25, v26, v27
	ds_read_b64 v[26:27], v139 offset:8448
	global_store_dwordx2 v[28:29], v[24:25], off
	v_lshl_add_u64 v[24:25], v[128:129], 2, s[0:1]
	s_waitcnt lgkmcnt(0)
	v_sub_f32_e32 v21, v21, v26
	v_sub_f32_e32 v20, v20, v26
	v_sub_f32_e32 v23, v23, v26
	v_sub_f32_e32 v22, v22, v26
	v_pk_mul_f32 v[22:23], v[26:27], v[22:23] op_sel:[1,0]
	v_pk_mul_f32 v[20:21], v[26:27], v[20:21] op_sel:[1,0]
	v_pk_fma_f32 v[22:23], v[50:51], v[22:23], v[54:55]
	v_pk_fma_f32 v[20:21], v[48:49], v[20:21], v[52:53]
	v_cndmask_b32_e32 v23, v147, v23, vcc
	v_cndmask_b32_e32 v22, v147, v22, vcc
	v_cndmask_b32_e32 v21, v147, v21, vcc
	v_cndmask_b32_e32 v20, v147, v20, vcc
	global_store_dwordx4 v[24:25], v[20:23], off nt
	v_lshl_add_u64 v[24:25], v[128:129], 1, s[4:5]
	v_add_u32_e32 v128, 0x18080, v60
	v_cvt_pk_bf16_f32 v20, v20, v21
	v_cvt_pk_bf16_f32 v21, v22, v23
	ds_read_b64 v[22:23], v139 offset:8576
	global_store_dwordx2 v[24:25], v[20:21], off
	v_lshl_add_u64 v[20:21], v[128:129], 2, s[0:1]
	s_waitcnt lgkmcnt(0)
	v_sub_f32_e32 v17, v17, v22
	v_sub_f32_e32 v16, v16, v22
	v_sub_f32_e32 v19, v19, v22
	v_sub_f32_e32 v18, v18, v22
	v_pk_mul_f32 v[18:19], v[22:23], v[18:19] op_sel:[1,0]
	v_pk_mul_f32 v[16:17], v[22:23], v[16:17] op_sel:[1,0]
	v_pk_fma_f32 v[18:19], v[50:51], v[18:19], v[54:55]
	v_pk_fma_f32 v[16:17], v[48:49], v[16:17], v[52:53]
	v_cndmask_b32_e32 v19, v147, v19, vcc
	v_cndmask_b32_e32 v18, v147, v18, vcc
	v_cndmask_b32_e32 v17, v147, v17, vcc
	v_cndmask_b32_e32 v16, v147, v16, vcc
	global_store_dwordx4 v[20:21], v[16:19], off nt
	v_lshl_add_u64 v[20:21], v[128:129], 1, s[4:5]
	v_add_u32_e32 v128, 0x40080, v60
	v_cvt_pk_bf16_f32 v16, v16, v17
	v_cvt_pk_bf16_f32 v17, v18, v19
	ds_read_b64 v[18:19], v139 offset:9216
	global_store_dwordx2 v[20:21], v[16:17], off
	s_waitcnt lgkmcnt(0)
	v_sub_f32_e32 v17, v77, v18
	v_sub_f32_e32 v16, v76, v18
	v_sub_f32_e32 v21, v79, v18
	v_sub_f32_e32 v20, v78, v18
	v_pk_mul_f32 v[20:21], v[18:19], v[20:21] op_sel:[1,0]
	v_pk_mul_f32 v[16:17], v[18:19], v[16:17] op_sel:[1,0]
	v_pk_fma_f32 v[18:19], v[50:51], v[20:21], v[54:55]
	v_pk_fma_f32 v[16:17], v[48:49], v[16:17], v[52:53]
	v_cndmask_b32_e32 v19, v147, v19, vcc
	v_cndmask_b32_e32 v18, v147, v18, vcc
	v_cndmask_b32_e32 v17, v147, v17, vcc
	v_cndmask_b32_e32 v16, v147, v16, vcc
	v_lshl_add_u64 v[20:21], v[128:129], 2, s[0:1]
	global_store_dwordx4 v[20:21], v[16:19], off nt
	v_lshl_add_u64 v[20:21], v[128:129], 1, s[4:5]
	v_add_u32_e32 v128, 0x48080, v60
	v_cvt_pk_bf16_f32 v16, v16, v17
	v_cvt_pk_bf16_f32 v17, v18, v19
	ds_read_b64 v[18:19], v139 offset:9344
	global_store_dwordx2 v[20:21], v[16:17], off
	s_waitcnt lgkmcnt(0)
	v_sub_f32_e32 v17, v73, v18
	v_sub_f32_e32 v16, v72, v18
	v_sub_f32_e32 v21, v75, v18
	v_sub_f32_e32 v20, v74, v18
	v_pk_mul_f32 v[20:21], v[18:19], v[20:21] op_sel:[1,0]
	v_pk_mul_f32 v[16:17], v[18:19], v[16:17] op_sel:[1,0]
	v_pk_fma_f32 v[18:19], v[50:51], v[20:21], v[54:55]
	v_pk_fma_f32 v[16:17], v[48:49], v[16:17], v[52:53]
	v_cndmask_b32_e32 v19, v147, v19, vcc
	v_cndmask_b32_e32 v18, v147, v18, vcc
	v_cndmask_b32_e32 v17, v147, v17, vcc
	v_cndmask_b32_e32 v16, v147, v16, vcc
	v_lshl_add_u64 v[20:21], v[128:129], 2, s[0:1]
	global_store_dwordx4 v[20:21], v[16:19], off nt
	v_lshl_add_u64 v[20:21], v[128:129], 1, s[4:5]
	v_add_u32_e32 v128, 0x50080, v60
	v_cvt_pk_bf16_f32 v16, v16, v17
	v_cvt_pk_bf16_f32 v17, v18, v19
	ds_read_b64 v[18:19], v139 offset:9472
	global_store_dwordx2 v[20:21], v[16:17], off
	s_waitcnt lgkmcnt(0)
	v_sub_f32_e32 v17, v69, v18
	v_sub_f32_e32 v16, v68, v18
	v_sub_f32_e32 v21, v71, v18
	v_sub_f32_e32 v20, v70, v18
	v_pk_mul_f32 v[20:21], v[18:19], v[20:21] op_sel:[1,0]
	v_pk_mul_f32 v[16:17], v[18:19], v[16:17] op_sel:[1,0]
	v_pk_fma_f32 v[18:19], v[50:51], v[20:21], v[54:55]
	v_pk_fma_f32 v[16:17], v[48:49], v[16:17], v[52:53]
	v_cndmask_b32_e32 v19, v147, v19, vcc
	v_cndmask_b32_e32 v18, v147, v18, vcc
	v_cndmask_b32_e32 v17, v147, v17, vcc
	v_cndmask_b32_e32 v16, v147, v16, vcc
	v_lshl_add_u64 v[20:21], v[128:129], 2, s[0:1]
	global_store_dwordx4 v[20:21], v[16:19], off nt
	v_lshl_add_u64 v[20:21], v[128:129], 1, s[4:5]
	v_add_u32_e32 v128, 0x58080, v60
	v_cvt_pk_bf16_f32 v16, v16, v17
	v_cvt_pk_bf16_f32 v17, v18, v19
	ds_read_b64 v[18:19], v139 offset:9600
	global_store_dwordx2 v[20:21], v[16:17], off
	s_waitcnt lgkmcnt(0)
	v_sub_f32_e32 v17, v65, v18
	v_sub_f32_e32 v16, v64, v18
	v_sub_f32_e32 v21, v67, v18
	v_sub_f32_e32 v20, v66, v18
	v_pk_mul_f32 v[20:21], v[18:19], v[20:21] op_sel:[1,0]
	v_pk_mul_f32 v[16:17], v[18:19], v[16:17] op_sel:[1,0]
	v_pk_fma_f32 v[18:19], v[50:51], v[20:21], v[54:55]
	v_pk_fma_f32 v[16:17], v[48:49], v[16:17], v[52:53]
	v_cndmask_b32_e32 v19, v147, v19, vcc
	v_cndmask_b32_e32 v18, v147, v18, vcc
	v_cndmask_b32_e32 v17, v147, v17, vcc
	v_cndmask_b32_e32 v16, v147, v16, vcc
	v_lshl_add_u64 v[20:21], v[128:129], 2, s[0:1]
	global_store_dwordx4 v[20:21], v[16:19], off nt
	s_nop 1
	v_cvt_pk_bf16_f32 v16, v16, v17
	v_cvt_pk_bf16_f32 v17, v18, v19
	v_lshl_add_u64 v[18:19], v[128:129], 1, s[4:5]
	global_store_dwordx2 v[18:19], v[16:17], off
	global_load_dwordx4 v[16:19], v[140:141], off offset:576
	global_load_dwordx4 v[20:23], v[142:143], off offset:576
	ds_read_b64 v[24:25], v139 offset:8192
	v_lshl_add_u32 v28, v146, 11, v138
	v_add_u32_e32 v128, 0x90, v28
	v_lshl_add_u64 v[26:27], v[128:129], 2, s[0:1]
	s_waitcnt lgkmcnt(0)
	v_sub_f32_e32 v13, v13, v24
	v_sub_f32_e32 v12, v12, v24
	v_sub_f32_e32 v15, v15, v24
	v_sub_f32_e32 v14, v14, v24
	v_pk_mul_f32 v[14:15], v[24:25], v[14:15] op_sel:[1,0]
	v_pk_mul_f32 v[12:13], v[24:25], v[12:13] op_sel:[1,0]
	v_lshl_add_u64 v[24:25], v[128:129], 1, s[4:5]
	v_add_u32_e32 v128, 0x8090, v28
	s_waitcnt vmcnt(0)
	v_pk_fma_f32 v[12:13], v[16:17], v[12:13], v[20:21]
	v_pk_fma_f32 v[14:15], v[18:19], v[14:15], v[22:23]
	v_cndmask_b32_e32 v13, v147, v13, vcc
	v_cndmask_b32_e32 v15, v147, v15, vcc
	v_cndmask_b32_e32 v14, v147, v14, vcc
	v_cndmask_b32_e32 v12, v147, v12, vcc
	global_store_dwordx4 v[26:27], v[12:15], off nt
	s_nop 1
	v_cvt_pk_bf16_f32 v12, v12, v13
	v_cvt_pk_bf16_f32 v13, v14, v15
	ds_read_b64 v[14:15], v139 offset:8320
	global_store_dwordx2 v[24:25], v[12:13], off
	v_lshl_add_u64 v[12:13], v[128:129], 2, s[0:1]
	s_waitcnt lgkmcnt(0)
	v_sub_f32_e32 v9, v9, v14
	v_sub_f32_e32 v8, v8, v14
	v_sub_f32_e32 v11, v11, v14
	v_sub_f32_e32 v10, v10, v14
	v_pk_mul_f32 v[10:11], v[14:15], v[10:11] op_sel:[1,0]
	v_pk_mul_f32 v[8:9], v[14:15], v[8:9] op_sel:[1,0]
	v_pk_fma_f32 v[10:11], v[18:19], v[10:11], v[22:23]
	v_pk_fma_f32 v[8:9], v[16:17], v[8:9], v[20:21]
	v_cndmask_b32_e32 v11, v147, v11, vcc
	v_cndmask_b32_e32 v10, v147, v10, vcc
	v_cndmask_b32_e32 v9, v147, v9, vcc
	v_cndmask_b32_e32 v8, v147, v8, vcc
	global_store_dwordx4 v[12:13], v[8:11], off nt
	v_lshl_add_u64 v[12:13], v[128:129], 1, s[4:5]
	v_add_u32_e32 v128, 0x10090, v28
	v_cvt_pk_bf16_f32 v8, v8, v9
	v_cvt_pk_bf16_f32 v9, v10, v11
	ds_read_b64 v[10:11], v139 offset:8448
	global_store_dwordx2 v[12:13], v[8:9], off
	v_lshl_add_u64 v[8:9], v[128:129], 2, s[0:1]
	s_waitcnt lgkmcnt(0)
	v_sub_f32_e32 v5, v5, v10
	v_sub_f32_e32 v4, v4, v10
	v_sub_f32_e32 v7, v7, v10
	v_sub_f32_e32 v6, v6, v10
	v_pk_mul_f32 v[6:7], v[10:11], v[6:7] op_sel:[1,0]
	v_pk_mul_f32 v[4:5], v[10:11], v[4:5] op_sel:[1,0]
	v_pk_fma_f32 v[6:7], v[18:19], v[6:7], v[22:23]
	v_pk_fma_f32 v[4:5], v[16:17], v[4:5], v[20:21]
	v_cndmask_b32_e32 v7, v147, v7, vcc
	v_cndmask_b32_e32 v6, v147, v6, vcc
	v_cndmask_b32_e32 v5, v147, v5, vcc
	v_cndmask_b32_e32 v4, v147, v4, vcc
	global_store_dwordx4 v[8:9], v[4:7], off nt
	v_lshl_add_u64 v[8:9], v[128:129], 1, s[4:5]
	v_add_u32_e32 v128, 0x18090, v28
	v_cvt_pk_bf16_f32 v4, v4, v5
	v_cvt_pk_bf16_f32 v5, v6, v7
	ds_read_b64 v[6:7], v139 offset:8576
	global_store_dwordx2 v[8:9], v[4:5], off
	v_lshl_add_u64 v[4:5], v[128:129], 2, s[0:1]
	s_waitcnt lgkmcnt(0)
	v_sub_f32_e32 v1, v1, v6
	v_sub_f32_e32 v0, v0, v6
	v_sub_f32_e32 v3, v3, v6
	v_sub_f32_e32 v2, v2, v6
	v_pk_mul_f32 v[2:3], v[6:7], v[2:3] op_sel:[1,0]
	v_pk_mul_f32 v[0:1], v[6:7], v[0:1] op_sel:[1,0]
	v_pk_fma_f32 v[2:3], v[18:19], v[2:3], v[22:23]
	v_pk_fma_f32 v[0:1], v[16:17], v[0:1], v[20:21]
	v_cndmask_b32_e32 v3, v147, v3, vcc
	v_cndmask_b32_e32 v2, v147, v2, vcc
	v_cndmask_b32_e32 v1, v147, v1, vcc
	v_cndmask_b32_e32 v0, v147, v0, vcc
	global_store_dwordx4 v[4:5], v[0:3], off nt
	v_lshl_add_u64 v[4:5], v[128:129], 1, s[4:5]
	v_add_u32_e32 v128, 0x40090, v28
	v_cvt_pk_bf16_f32 v0, v0, v1
	v_cvt_pk_bf16_f32 v1, v2, v3
	ds_read_b64 v[2:3], v139 offset:9216
	global_store_dwordx2 v[4:5], v[0:1], off
	s_waitcnt lgkmcnt(0)
	v_sub_f32_e32 v1, v45, v2
	v_sub_f32_e32 v0, v44, v2
	v_sub_f32_e32 v5, v47, v2
	v_sub_f32_e32 v4, v46, v2
	v_pk_mul_f32 v[4:5], v[2:3], v[4:5] op_sel:[1,0]
	v_pk_mul_f32 v[0:1], v[2:3], v[0:1] op_sel:[1,0]
	v_pk_fma_f32 v[2:3], v[18:19], v[4:5], v[22:23]
	v_pk_fma_f32 v[0:1], v[16:17], v[0:1], v[20:21]
	v_cndmask_b32_e32 v3, v147, v3, vcc
	v_cndmask_b32_e32 v2, v147, v2, vcc
	v_cndmask_b32_e32 v1, v147, v1, vcc
	v_cndmask_b32_e32 v0, v147, v0, vcc
	v_lshl_add_u64 v[4:5], v[128:129], 2, s[0:1]
	global_store_dwordx4 v[4:5], v[0:3], off nt
	v_lshl_add_u64 v[4:5], v[128:129], 1, s[4:5]
	v_add_u32_e32 v128, 0x48090, v28
	v_cvt_pk_bf16_f32 v0, v0, v1
	v_cvt_pk_bf16_f32 v1, v2, v3
	ds_read_b64 v[2:3], v139 offset:9344
	global_store_dwordx2 v[4:5], v[0:1], off
	s_waitcnt lgkmcnt(0)
	v_sub_f32_e32 v1, v41, v2
	v_sub_f32_e32 v0, v40, v2
	v_sub_f32_e32 v5, v43, v2
	v_sub_f32_e32 v4, v42, v2
	v_pk_mul_f32 v[4:5], v[2:3], v[4:5] op_sel:[1,0]
	v_pk_mul_f32 v[0:1], v[2:3], v[0:1] op_sel:[1,0]
	v_pk_fma_f32 v[2:3], v[18:19], v[4:5], v[22:23]
	v_pk_fma_f32 v[0:1], v[16:17], v[0:1], v[20:21]
	v_cndmask_b32_e32 v3, v147, v3, vcc
	v_cndmask_b32_e32 v2, v147, v2, vcc
	v_cndmask_b32_e32 v1, v147, v1, vcc
	v_cndmask_b32_e32 v0, v147, v0, vcc
	v_lshl_add_u64 v[4:5], v[128:129], 2, s[0:1]
	global_store_dwordx4 v[4:5], v[0:3], off nt
	v_lshl_add_u64 v[4:5], v[128:129], 1, s[4:5]
	v_add_u32_e32 v128, 0x50090, v28
	v_cvt_pk_bf16_f32 v0, v0, v1
	v_cvt_pk_bf16_f32 v1, v2, v3
	ds_read_b64 v[2:3], v139 offset:9472
	global_store_dwordx2 v[4:5], v[0:1], off
	s_waitcnt lgkmcnt(0)
	v_sub_f32_e32 v1, v37, v2
	v_sub_f32_e32 v0, v36, v2
	v_sub_f32_e32 v5, v39, v2
	v_sub_f32_e32 v4, v38, v2
	v_pk_mul_f32 v[4:5], v[2:3], v[4:5] op_sel:[1,0]
	v_pk_mul_f32 v[0:1], v[2:3], v[0:1] op_sel:[1,0]
	v_pk_fma_f32 v[2:3], v[18:19], v[4:5], v[22:23]
	v_pk_fma_f32 v[0:1], v[16:17], v[0:1], v[20:21]
	v_cndmask_b32_e32 v3, v147, v3, vcc
	v_cndmask_b32_e32 v2, v147, v2, vcc
	v_cndmask_b32_e32 v1, v147, v1, vcc
	v_cndmask_b32_e32 v0, v147, v0, vcc
	v_lshl_add_u64 v[4:5], v[128:129], 2, s[0:1]
	global_store_dwordx4 v[4:5], v[0:3], off nt
	v_lshl_add_u64 v[4:5], v[128:129], 1, s[4:5]
	v_add_u32_e32 v128, 0x58090, v28
	v_cvt_pk_bf16_f32 v0, v0, v1
	v_cvt_pk_bf16_f32 v1, v2, v3
	ds_read_b64 v[2:3], v139 offset:9600
	global_store_dwordx2 v[4:5], v[0:1], off
	s_waitcnt lgkmcnt(0)
	v_sub_f32_e32 v1, v33, v2
	v_sub_f32_e32 v0, v32, v2
	v_sub_f32_e32 v5, v35, v2
	v_sub_f32_e32 v4, v34, v2
	v_pk_mul_f32 v[4:5], v[2:3], v[4:5] op_sel:[1,0]
	v_pk_mul_f32 v[0:1], v[2:3], v[0:1] op_sel:[1,0]
	v_pk_fma_f32 v[2:3], v[18:19], v[4:5], v[22:23]
	v_pk_fma_f32 v[0:1], v[16:17], v[0:1], v[20:21]
	v_cndmask_b32_e32 v3, v147, v3, vcc
	v_cndmask_b32_e32 v2, v147, v2, vcc
	v_cndmask_b32_e32 v1, v147, v1, vcc
	v_cndmask_b32_e32 v0, v147, v0, vcc
	v_lshl_add_u64 v[4:5], v[128:129], 2, s[0:1]
	global_store_dwordx4 v[4:5], v[0:3], off nt
	s_nop 1
	v_cvt_pk_bf16_f32 v0, v0, v1
	v_cvt_pk_bf16_f32 v1, v2, v3
	v_lshl_add_u64 v[2:3], v[128:129], 1, s[4:5]
	global_store_dwordx2 v[2:3], v[0:1], off
